# T3: GEMM1 tail queue latency: first fetch_add issued under the last unit's store drain; exhausted-queue detected from an agent-scope counter read taken under the quadrant epilogue's loads
# baseline (speedup 1.0000x reference)
; __device__ __forceinline__ void gemm1_tail_quadrant(LAS unsigned char* lds, const f16* A, const f16* Bt, unsigned char* ws, int pm, int pn, int ai, int bj) {
;     ...
;     const float* SS = (const float*)(ws + WS_SS); f16* Z = (f16*)(ws + WS_Z);
;     const int row0 = pm * 256 + ai * 128 + wr * 64 + fr;
;     f32x4 part[4];
; #pragma unroll
;     for (int m = 0; m < 4; ++m) part[m] = *(const f32x4*)(SS + (size_t)(row0 + m * 16) * 16 + 4 * fq);
; #pragma unroll
;     for (int m = 0; m < 4; ++m) {
;         float t = (part[m][0] + part[m][1]) + (part[m][2] + part[m][3]);
;         t = sum_fq(t);
;         const float rs = __builtin_amdgcn_rsqf(t * (1.0f / 1024.0f) + EPS);
;         const int row = row0 + m * 16;
;         float v[8];
; #pragma unroll
;         for (int e = 0; e < 8; ++e) v[e] = acc[m][e >> 2][e & 3] * rs;
;         const int cg8 = 8 * (wc & 1) + 4 * bj + fq;
;         f16* p = Z + (((size_t)(((row >> 12) * 4 + (pn - 7)) * 16 + cg8) * 4096 + (row & 4095)) * 2 + (wc >> 1)) * 8;
;         *(u32x4*)p = pack8(v);
;     }
;     asm volatile("s_waitcnt vmcnt(0)" ::: "memory");
;     __syncthreads();
.LBB0_319:
	s_mov_b64 s[36:37], exec
	s_lshl_b64 s[34:35], s[82:83], 21
	v_mov_b32_e32 v72, 0
	s_mov_b64 exec, s[34:35]
	global_load_dword v255, v72, s[0:1] sc1
	s_mov_b64 exec, s[36:37]
	s_mov_b32 s101, 2
	s_and_b32 s4, 0xffff, s14
	s_lshl_b32 s6, s13, 7
	s_lshl_b32 s4, s4, 8
	s_or_b32 s4, s4, s6
	s_add_i32 s4, s4, s31
	v_or_b32_e32 v54, s4, v23
	v_readlane_b32 s6, v254, 4
	v_mov_b32_e32 v23, v195
	v_readlane_b32 s7, v254, 5
	v_ashrrev_i32_e32 v55, 31, v54
	v_lshlrev_b64 v[24:25], 6, v[54:55]
	v_lshl_add_u64 v[22:23], s[6:7], 0, v[22:23]
	v_lshl_add_u64 v[24:25], v[22:23], 0, v[24:25]
	global_load_dwordx4 v[46:49], v[24:25], off
	v_or_b32_e32 v24, 16, v54
	v_ashrrev_i32_e32 v25, 31, v24
	v_lshlrev_b64 v[24:25], 6, v[24:25]
	v_lshl_add_u64 v[24:25], v[22:23], 0, v[24:25]
	global_load_dwordx4 v[50:53], v[24:25], off
	v_or_b32_e32 v24, 32, v54
	v_ashrrev_i32_e32 v25, 31, v24
	v_lshlrev_b64 v[24:25], 6, v[24:25]
	v_lshl_add_u64 v[24:25], v[22:23], 0, v[24:25]
	global_load_dwordx4 v[30:33], v[24:25], off
	v_or_b32_e32 v24, 48, v54
	v_ashrrev_i32_e32 v25, 31, v24
	v_lshlrev_b64 v[24:25], 6, v[24:25]
	v_lshl_add_u64 v[22:23], v[22:23], 0, v[24:25]
	global_load_dwordx4 v[22:25], v[22:23], off
	s_ashr_i32 s4, s4, 10
	s_and_b32 s5, 0xffff, s15
	s_lshl_b32 s6, s12, 3
	s_and_b32 s4, s4, 0xffffffc
	s_and_b32 s6, s6, 8
	s_lshl_b32 s7, s11, 2
	s_add_i32 s5, s5, s4
	s_or_b32 s6, s6, s7
	s_lshl_b32 s4, s5, 4
	s_or_b32 s4, s4, s6
	s_addk_i32 s4, 0xff90
	v_or_b32_e32 v42, s4, v44
	v_mov_b32_e32 v44, v54
	v_and_b32_e32 v45, 0xfcf, v44
	v_ashrrev_i32_e32 v43, 31, v42
	v_lshlrev_b64 v[42:43], 13, v[42:43]
	s_lshr_b32 s4, s10, 1
	s_lshl_b32 s4, s4, 12
	v_or3_b32 v42, v42, s4, v45
	s_mov_b64 s[4:5], 0
	s_waitcnt vmcnt(0)
	v_add_f32_e32 v44, v46, v47
	v_add_f32_e32 v46, v48, v49
	v_add_f32_e32 v44, v44, v46
	v_mov_b32_e32 v46, v44
	s_nop 1
	v_permlane16_swap_b32_e32 v44, v46
	v_add_f32_e32 v44, v44, v46
	v_mov_b32_e32 v46, v44
	s_nop 1
	v_permlane32_swap_b32_e32 v44, v46
	v_add_f32_e32 v44, v44, v46
	v_fmamk_f32 v44, v44, 0x3a800000, v1
	v_rsq_f32_e32 v44, v44
	v_lshl_add_u64 v[46:47], v[42:43], 4, s[16:17]
	v_fma_mixlo_f16 v45, v38, v44, 0
	v_mov_b32_e32 v38, v39
	v_mov_b32_e32 v39, v40
	v_pk_mov_b32 v[40:41], v[40:41], v[34:35] op_sel:[1,0]
	v_mov_b32_e32 v34, v35
	v_mov_b32_e32 v35, v36
	v_pk_mul_f32 v[38:39], v[38:39], v[44:45] op_sel_hi:[1,0]
	v_pk_mul_f32 v[40:41], v[40:41], v[44:45] op_sel_hi:[1,0]
	v_pk_mul_f32 v[34:35], v[34:35], v[44:45] op_sel_hi:[1,0]
	v_cvt_pk_f16_f32 v39, v38, v39
	v_cvt_pk_f16_f32 v40, v40, v41
	v_cvt_pk_f16_f32 v34, v34, v35
	v_pack_b32_f16 v38, v45, v39
	v_alignbit_b32 v39, v40, v39, 16
	v_alignbit_b32 v40, v34, v40, 16
	v_lshrrev_b32_e32 v41, 16, v34
	v_add_f32_e32 v34, v50, v51
	v_add_f32_e32 v35, v52, v53
	v_add_f32_e32 v34, v34, v35
	v_mov_b32_e32 v35, v34
	s_nop 1
	v_permlane16_swap_b32_e32 v34, v35
	v_add_f32_e32 v34, v34, v35
	v_mov_b32_e32 v35, v34
	s_nop 1
	v_permlane32_swap_b32_e32 v34, v35
	v_add_f32_e32 v34, v34, v35
	v_fmamk_f32 v34, v34, 0x3a800000, v1
	v_rsq_f32_e32 v36, v34
	v_fma_mixhi_f16 v41, v37, v44, 0
	v_or_b32_e32 v34, 16, v42
	v_mov_b32_e32 v35, v43
	v_fma_mixlo_f16 v37, v26, v36, 0
	v_mov_b32_e32 v26, v27
	v_mov_b32_e32 v27, v28
	v_pk_mov_b32 v[28:29], v[28:29], v[18:19] op_sel:[1,0]
	v_mov_b32_e32 v18, v19
	v_mov_b32_e32 v19, v20
	v_pk_mul_f32 v[26:27], v[26:27], v[36:37] op_sel_hi:[1,0]
	v_pk_mul_f32 v[28:29], v[28:29], v[36:37] op_sel_hi:[1,0]
	v_pk_mul_f32 v[18:19], v[18:19], v[36:37] op_sel_hi:[1,0]
	v_cvt_pk_f16_f32 v27, v26, v27
	v_cvt_pk_f16_f32 v28, v28, v29
	v_cvt_pk_f16_f32 v18, v18, v19
	v_pack_b32_f16 v26, v37, v27
	v_alignbit_b32 v27, v28, v27, 16
	v_alignbit_b32 v28, v18, v28, 16
	v_lshrrev_b32_e32 v29, 16, v18
	v_add_f32_e32 v18, v30, v31
	v_add_f32_e32 v19, v32, v33
	v_add_f32_e32 v18, v18, v19
	v_mov_b32_e32 v19, v18
	s_nop 1
	v_permlane16_swap_b32_e32 v18, v19
	v_add_f32_e32 v18, v18, v19
	v_mov_b32_e32 v19, v18
	s_nop 1
	v_permlane32_swap_b32_e32 v18, v19
	v_add_f32_e32 v18, v18, v19
	v_fmamk_f32 v18, v18, 0x3a800000, v1
	v_rsq_f32_e32 v18, v18
	v_fma_mixhi_f16 v29, v21, v36, 0
	v_or_b32_e32 v20, 32, v42
	v_mov_b32_e32 v21, v43
	v_fma_mixlo_f16 v19, v14, v18, 0
	v_mov_b32_e32 v14, v15
	v_mov_b32_e32 v15, v16
	v_pk_mov_b32 v[16:17], v[16:17], v[10:11] op_sel:[1,0]
	v_mov_b32_e32 v10, v11
	v_mov_b32_e32 v11, v12
	v_pk_mul_f32 v[14:15], v[14:15], v[18:19] op_sel_hi:[1,0]
	v_pk_mul_f32 v[16:17], v[16:17], v[18:19] op_sel_hi:[1,0]
	v_pk_mul_f32 v[10:11], v[10:11], v[18:19] op_sel_hi:[1,0]
	v_cvt_pk_f16_f32 v15, v14, v15
	v_cvt_pk_f16_f32 v16, v16, v17
	v_cvt_pk_f16_f32 v10, v10, v11
	v_pack_b32_f16 v14, v19, v15
	v_alignbit_b32 v15, v16, v15, 16
	v_alignbit_b32 v16, v10, v16, 16
	v_lshrrev_b32_e32 v17, 16, v10
	v_add_f32_e32 v10, v22, v23
	v_add_f32_e32 v11, v24, v25
	v_add_f32_e32 v10, v10, v11
	v_mov_b32_e32 v11, v10
	s_nop 1
	v_permlane16_swap_b32_e32 v10, v11
	v_add_f32_e32 v10, v10, v11
	v_mov_b32_e32 v11, v10
	s_nop 1
	v_permlane32_swap_b32_e32 v10, v11
	v_add_f32_e32 v10, v10, v11
	v_fmamk_f32 v10, v10, 0x3a800000, v1
	v_rsq_f32_e32 v10, v10
	v_or_b32_e32 v42, 48, v42
	v_lshl_add_u64 v[34:35], v[34:35], 4, s[16:17]
	v_lshl_add_u64 v[20:21], v[20:21], 4, s[16:17]
	v_fma_mixlo_f16 v11, v2, v10, 0
	v_mov_b32_e32 v2, v3
	v_mov_b32_e32 v3, v4
	v_pk_mov_b32 v[4:5], v[4:5], v[6:7] op_sel:[1,0]
	v_pk_mul_f32 v[2:3], v[2:3], v[10:11] op_sel_hi:[1,0]
	v_pk_mul_f32 v[4:5], v[4:5], v[10:11] op_sel_hi:[1,0]
	v_cvt_pk_f16_f32 v3, v2, v3
	v_cvt_pk_f16_f32 v6, v4, v5
	v_mov_b32_e32 v4, v7
	v_mov_b32_e32 v5, v8
	v_pk_mul_f32 v[4:5], v[4:5], v[10:11] op_sel_hi:[1,0]
	v_fma_mixhi_f16 v17, v13, v18, 0
	v_cvt_pk_f16_f32 v5, v4, v5
	v_alignbit_b32 v4, v5, v6, 16
	v_lshrrev_b32_e32 v5, 16, v5
	v_lshl_add_u64 v[12:13], v[42:43], 4, s[16:17]
	v_pack_b32_f16 v2, v11, v3
	v_alignbit_b32 v3, v6, v3, 16
	v_fma_mixhi_f16 v5, v9, v10, 0
	global_store_dwordx4 v[46:47], v[38:41], off
	global_store_dwordx4 v[34:35], v[26:29], off
	global_store_dwordx4 v[20:21], v[14:17], off
	global_store_dwordx4 v[12:13], v[2:5], off
	s_waitcnt vmcnt(0)
	s_barrier

; __global__ void __launch_bounds__(NTHREADS, 2) hymba_fwd(Args a) {
;     ...
;                 for (;;) {
;                     if (threadIdx.x == 0) *qslot = __hip_atomic_fetch_add(tailq, 1u, __ATOMIC_RELAXED, __HIP_MEMORY_SCOPE_AGENT);
;                     __syncthreads();
;                     const unsigned q = *qslot;
;                     __syncthreads();
;                     if (q >= 256u) break;
.LBB0_321:
	s_and_saveexec_b64 s[4:5], s[82:83]
	s_cbranch_execz .LBB0_325
	s_waitcnt vmcnt(0)
	s_cmp_eq_u32 s101, 1
	s_cbranch_scc0 .Lt3_n1
	v_readlane_b32 s6, v255, 20
	s_branch .Lt3_have
.Lt3_n1:
	s_cmp_eq_u32 s101, 2
	s_cbranch_scc0 .Lt3_fetch
	v_readlane_b32 s6, v255, 21
	s_nop 3
	s_cmp_ge_u32 s6, 0x100
	s_cbranch_scc1 .Lt3_have
.Lt3_fetch:
	v_mov_b32_e32 v3, 1
	global_atomic_add v3, v195, v3, s[0:1] sc0
	s_waitcnt vmcnt(0)
	v_readfirstlane_b32 s6, v3
.Lt3_have:
	s_mov_b32 s101, 0
	v_mov_b32_e32 v2, 0
	s_nop 1
	v_add_u32_e32 v2, s6, v2
	v_readlane_b32 s6, v254, 47
	s_nop 1
	v_mov_b32_e32 v3, s6
	ds_write_b32 v3, v2
